# write-through (sc1) stores for the retention KV states (M1) and the M2 scan outputs: the cross-XCD barrier's L2 write-back after M1 and M2 finds less dirty data
# speedup vs baseline: 1.0232x; 1.0064x over previous
; __device__ __forceinline__ unsigned pk2(float lo, float hi) { return pg8::cvt_pk_bf16(lo, hi); }
; __device__ __forceinline__ float ret_lg2(int h) { return log2f(1.0f - exp2f(-5.0f - (float)h)); }
; __device__ __forceinline__ void m2_scans(const Args& a, int l, int tid, int G) {
;     ...
;     for (int r = gt; r < 8 * 8192; r += NRT) {
;         const int bh = r >> 13, ed = (r & 8191) * 2, h = bh & 3;
;         const float gC = exp2f(128.0f * ret_lg2(h));
;         const float* p = (const float*)(a.ws + WS_KV) + (size_t)bh * 64 * 16384 + ed; bf16* pb = (bf16*)(a.ws + WS_PB) + (size_t)bh * 64 * 16384 + ed;
;         float S0 = 0.f, S1 = 0.f;
;         for (int nb = 0; nb < 64; nb += 32) {
;             f32x2 v[32];
; #pragma unroll
;             for (int j = 0; j < 32; ++j) v[j] = *(const f32x2*)(p + (size_t)(nb + j) * 16384);
; #pragma unroll
;             for (int j = 0; j < 32; ++j) { *(unsigned*)(pb + (size_t)(nb + j) * 16384) = pk2(S0, S1); S0 = fmaf(gC, S0, v[j].x); S1 = fmaf(gC, S1, v[j].y); }
;         }
.LBB0_1377:
	v_cndmask_b32_e64 v8, 0, 1, s[4:5]
	s_or_b32 s74, s82, 0x4000
	v_cmp_ne_u32_e32 vcc, 1, v8
	v_lshl_add_u64 v[8:9], s[82:83], 2, v[2:3]
	s_mov_b32 s75, s83
	s_or_b32 s76, s82, 0x8000
	global_load_dwordx2 v[8:9], v[8:9], off
	v_lshl_add_u64 v[10:11], s[74:75], 2, v[2:3]
	s_mov_b32 s77, s83
	s_or_b32 s88, s82, 0xc000
	global_load_dwordx2 v[10:11], v[10:11], off
	v_lshl_add_u64 v[12:13], s[76:77], 2, v[2:3]
	s_mov_b32 s89, s83
	s_or_b32 s90, s82, 0x10000
	global_load_dwordx2 v[12:13], v[12:13], off
	v_lshl_add_u64 v[14:15], s[88:89], 2, v[2:3]
	s_mov_b32 s91, s83
	s_or_b32 s24, s82, 0x14000
	global_load_dwordx2 v[14:15], v[14:15], off
	v_lshl_add_u64 v[16:17], s[90:91], 2, v[2:3]
	s_mov_b32 s25, s83
	s_or_b32 s0, s82, 0x18000
	global_load_dwordx2 v[16:17], v[16:17], off
	v_lshl_add_u64 v[18:19], s[24:25], 2, v[2:3]
	s_mov_b32 s1, s83
	s_or_b32 s26, s82, 0x1c000
	global_load_dwordx2 v[18:19], v[18:19], off
	v_lshl_add_u64 v[20:21], s[0:1], 2, v[2:3]
	s_mov_b32 s27, s83
	s_or_b32 s78, s82, 0x20000
	global_load_dwordx2 v[20:21], v[20:21], off
	v_lshl_add_u64 v[22:23], s[26:27], 2, v[2:3]
	s_mov_b32 s79, s83
	s_or_b32 s80, s82, 0x24000
	s_or_b32 s52, s82, 0x2c000
	s_or_b32 s56, s82, 0x34000
	global_load_dwordx2 v[22:23], v[22:23], off
	v_lshl_add_u64 v[24:25], s[78:79], 2, v[2:3]
	s_mov_b32 s81, s83
	s_mov_b32 s53, s83
	s_mov_b32 s57, s83
	s_or_b32 s72, s82, 0x28000
	global_load_dwordx2 v[24:25], v[24:25], off
	v_lshl_add_u64 v[26:27], s[80:81], 2, v[2:3]
	s_mov_b32 s73, s83
	v_lshl_add_u64 v[30:31], s[52:53], 2, v[2:3]
	v_lshl_add_u64 v[34:35], s[56:57], 2, v[2:3]
	global_load_dwordx2 v[28:29], v[26:27], off
	s_or_b32 s54, s82, 0x30000
	global_load_dwordx2 v[30:31], v[30:31], off
	s_mov_b32 s55, s83
	global_load_dwordx2 v[34:35], v[34:35], off
	v_lshl_add_u64 v[26:27], s[72:73], 2, v[2:3]
	global_load_dwordx2 v[26:27], v[26:27], off
	v_lshl_add_u64 v[32:33], s[54:55], 2, v[2:3]
	s_or_b32 s58, s82, 0x38000
	global_load_dwordx2 v[32:33], v[32:33], off
	s_mov_b32 s59, s83
	s_or_b32 s60, s82, 0x3c000
	v_lshl_add_u64 v[36:37], s[58:59], 2, v[2:3]
	s_mov_b32 s61, s83
	s_or_b32 s62, s82, 0x40000
	global_load_dwordx2 v[36:37], v[36:37], off
	v_lshl_add_u64 v[38:39], s[60:61], 2, v[2:3]
	s_mov_b32 s63, s83
	s_or_b32 s64, s82, 0x44000
	global_load_dwordx2 v[38:39], v[38:39], off
	v_lshl_add_u64 v[40:41], s[62:63], 2, v[2:3]
	s_mov_b32 s65, s83
	s_or_b32 s66, s82, 0x48000
	global_load_dwordx2 v[40:41], v[40:41], off
	v_lshl_add_u64 v[42:43], s[64:65], 2, v[2:3]
	s_mov_b32 s67, s83
	s_or_b32 s68, s82, 0x4c000
	global_load_dwordx2 v[42:43], v[42:43], off
	v_lshl_add_u64 v[48:49], s[66:67], 2, v[2:3]
	s_mov_b32 s69, s83
	s_or_b32 s70, s82, 0x50000
	global_load_dwordx2 v[48:49], v[48:49], off
	v_lshl_add_u64 v[50:51], s[68:69], 2, v[2:3]
	s_mov_b32 s71, s83
	s_or_b32 s50, s82, 0x54000
	global_load_dwordx2 v[50:51], v[50:51], off
	v_lshl_add_u64 v[52:53], s[70:71], 2, v[2:3]
	s_mov_b32 s51, s83
	s_or_b32 s6, s82, 0x58000
	global_load_dwordx2 v[52:53], v[52:53], off
	v_lshl_add_u64 v[54:55], s[50:51], 2, v[2:3]
	s_mov_b32 s7, s83
	s_or_b32 s28, s82, 0x5c000
	global_load_dwordx2 v[54:55], v[54:55], off
	v_lshl_add_u64 v[56:57], s[6:7], 2, v[2:3]
	s_mov_b32 s29, s83
	s_or_b32 s30, s82, 0x60000
	global_load_dwordx2 v[56:57], v[56:57], off
	v_lshl_add_u64 v[58:59], s[28:29], 2, v[2:3]
	s_mov_b32 s31, s83
	s_or_b32 s34, s82, 0x64000
	global_load_dwordx2 v[58:59], v[58:59], off
	v_lshl_add_u64 v[60:61], s[30:31], 2, v[2:3]
	s_mov_b32 s35, s83
	s_or_b32 s40, s82, 0x68000
	global_load_dwordx2 v[60:61], v[60:61], off
	v_lshl_add_u64 v[62:63], s[34:35], 2, v[2:3]
	s_mov_b32 s41, s83
	s_or_b32 s42, s82, 0x6c000
	global_load_dwordx2 v[62:63], v[62:63], off
	v_lshl_add_u64 v[64:65], s[40:41], 2, v[2:3]
	s_mov_b32 s43, s83
	s_or_b32 s44, s82, 0x70000
	global_load_dwordx2 v[64:65], v[64:65], off
	v_lshl_add_u64 v[66:67], s[42:43], 2, v[2:3]
	s_mov_b32 s45, s83
	s_or_b32 s46, s82, 0x74000
	global_load_dwordx2 v[66:67], v[66:67], off
	v_lshl_add_u64 v[68:69], s[44:45], 2, v[2:3]
	s_mov_b32 s47, s83
	s_or_b32 s48, s82, 0x78000
	global_load_dwordx2 v[68:69], v[68:69], off
	v_lshl_add_u64 v[70:71], s[46:47], 2, v[2:3]
	s_mov_b32 s49, s83
	s_or_b32 s4, s82, 0x7c000
	global_load_dwordx2 v[70:71], v[70:71], off
	v_lshl_add_u64 v[72:73], s[48:49], 2, v[2:3]
	s_mov_b32 s5, s83
	global_load_dwordx2 v[72:73], v[72:73], off
	v_lshl_add_u64 v[74:75], s[4:5], 2, v[2:3]
	global_load_dwordx2 v[74:75], v[74:75], off
	v_cvt_pk_bf16_f32 v47, v6, v7
	v_lshl_add_u64 v[76:77], s[82:83], 1, v[4:5]
	s_waitcnt vmcnt(31)
	v_pk_fma_f32 v[6:7], v[0:1], v[6:7], v[8:9]
	global_store_dword v[76:77], v47, off sc1
	v_lshl_add_u64 v[76:77], s[74:75], 1, v[4:5]
	v_cvt_pk_bf16_f32 v8, v6, v7
	s_waitcnt vmcnt(31)
	v_pk_fma_f32 v[6:7], v[0:1], v[6:7], v[10:11]
	v_lshl_add_u64 v[78:79], s[76:77], 1, v[4:5]
	global_store_dword v[76:77], v8, off sc1
	v_cvt_pk_bf16_f32 v8, v6, v7
	s_waitcnt vmcnt(31)
	v_pk_fma_f32 v[6:7], v[0:1], v[6:7], v[12:13]
	v_lshl_add_u64 v[80:81], s[88:89], 1, v[4:5]
	global_store_dword v[78:79], v8, off sc1
	v_cvt_pk_bf16_f32 v8, v6, v7
	s_waitcnt vmcnt(31)
	v_pk_fma_f32 v[6:7], v[0:1], v[6:7], v[14:15]
	v_lshl_add_u64 v[82:83], s[90:91], 1, v[4:5]
	global_store_dword v[80:81], v8, off sc1
	v_cvt_pk_bf16_f32 v8, v6, v7
	s_waitcnt vmcnt(31)
; __device__ __forceinline__ unsigned pk2(float lo, float hi) { return pg8::cvt_pk_bf16(lo, hi); }
; __device__ __forceinline__ void m2_scans(const Args& a, int l, int tid, int G) {
;     ...
;     for (int r = gt; r < 8 * 8192; r += NRT) {
;     ...
;             for (int j = 0; j < 32; ++j) v[j] = *(const f32x2*)(p + (size_t)(nb + j) * 16384);
; #pragma unroll
;             for (int j = 0; j < 32; ++j) { *(unsigned*)(pb + (size_t)(nb + j) * 16384) = pk2(S0, S1); S0 = fmaf(gC, S0, v[j].x); S1 = fmaf(gC, S1, v[j].y); }
;         }
;     }
	v_pk_fma_f32 v[6:7], v[0:1], v[6:7], v[16:17]
	v_lshl_add_u64 v[84:85], s[24:25], 1, v[4:5]
	global_store_dword v[82:83], v8, off sc1
	v_cvt_pk_bf16_f32 v8, v6, v7
	s_waitcnt vmcnt(31)
	v_pk_fma_f32 v[6:7], v[0:1], v[6:7], v[18:19]
	v_lshl_add_u64 v[86:87], s[0:1], 1, v[4:5]
	global_store_dword v[84:85], v8, off sc1
	v_cvt_pk_bf16_f32 v8, v6, v7
	s_waitcnt vmcnt(31)
	v_pk_fma_f32 v[6:7], v[0:1], v[6:7], v[20:21]
	v_lshl_add_u64 v[88:89], s[26:27], 1, v[4:5]
	global_store_dword v[86:87], v8, off sc1
	v_cvt_pk_bf16_f32 v8, v6, v7
	s_waitcnt vmcnt(31)
	v_pk_fma_f32 v[6:7], v[0:1], v[6:7], v[22:23]
	v_lshl_add_u64 v[90:91], s[78:79], 1, v[4:5]
	global_store_dword v[88:89], v8, off sc1
	v_cvt_pk_bf16_f32 v8, v6, v7
	s_waitcnt vmcnt(31)
	v_pk_fma_f32 v[6:7], v[0:1], v[6:7], v[24:25]
	v_lshl_add_u64 v[92:93], s[80:81], 1, v[4:5]
	global_store_dword v[90:91], v8, off sc1
	v_cvt_pk_bf16_f32 v8, v6, v7
	s_waitcnt vmcnt(31)
	v_pk_fma_f32 v[6:7], v[0:1], v[6:7], v[28:29]
	global_store_dword v[92:93], v8, off sc1
	v_cvt_pk_bf16_f32 v10, v6, v7
	v_lshl_add_u64 v[8:9], s[72:73], 1, v[4:5]
	s_waitcnt vmcnt(29)
	v_pk_fma_f32 v[6:7], v[0:1], v[6:7], v[26:27]
	global_store_dword v[8:9], v10, off sc1
	v_lshl_add_u64 v[8:9], s[52:53], 1, v[4:5]
	v_cvt_pk_bf16_f32 v26, v6, v7
	v_pk_fma_f32 v[6:7], v[0:1], v[6:7], v[30:31]
	v_lshl_add_u64 v[10:11], s[54:55], 1, v[4:5]
	global_store_dword v[8:9], v26, off sc1
	v_cvt_pk_bf16_f32 v8, v6, v7
	s_waitcnt vmcnt(30)
	v_pk_fma_f32 v[6:7], v[0:1], v[6:7], v[32:33]
	v_lshl_add_u64 v[12:13], s[56:57], 1, v[4:5]
	global_store_dword v[10:11], v8, off sc1
	v_cvt_pk_bf16_f32 v8, v6, v7
	v_pk_fma_f32 v[6:7], v[0:1], v[6:7], v[34:35]
	v_lshl_add_u64 v[14:15], s[58:59], 1, v[4:5]
	global_store_dword v[12:13], v8, off sc1
	v_cvt_pk_bf16_f32 v8, v6, v7
	s_waitcnt vmcnt(31)
	v_pk_fma_f32 v[6:7], v[0:1], v[6:7], v[36:37]
	v_lshl_add_u64 v[16:17], s[60:61], 1, v[4:5]
	global_store_dword v[14:15], v8, off sc1
	v_cvt_pk_bf16_f32 v8, v6, v7
	s_waitcnt vmcnt(31)
	v_pk_fma_f32 v[6:7], v[0:1], v[6:7], v[38:39]
	v_lshl_add_u64 v[18:19], s[62:63], 1, v[4:5]
	global_store_dword v[16:17], v8, off sc1
	v_cvt_pk_bf16_f32 v8, v6, v7
	s_waitcnt vmcnt(31)
	v_pk_fma_f32 v[6:7], v[0:1], v[6:7], v[40:41]
	v_lshl_add_u64 v[20:21], s[64:65], 1, v[4:5]
	global_store_dword v[18:19], v8, off sc1
	v_cvt_pk_bf16_f32 v8, v6, v7
	s_waitcnt vmcnt(31)
	v_pk_fma_f32 v[6:7], v[0:1], v[6:7], v[42:43]
	v_lshl_add_u64 v[22:23], s[66:67], 1, v[4:5]
	global_store_dword v[20:21], v8, off sc1
	v_cvt_pk_bf16_f32 v8, v6, v7
	s_waitcnt vmcnt(31)
	v_pk_fma_f32 v[6:7], v[0:1], v[6:7], v[48:49]
	v_lshl_add_u64 v[24:25], s[68:69], 1, v[4:5]
	global_store_dword v[22:23], v8, off sc1
	v_cvt_pk_bf16_f32 v8, v6, v7
	s_waitcnt vmcnt(31)
	v_pk_fma_f32 v[6:7], v[0:1], v[6:7], v[50:51]
	v_lshl_add_u64 v[28:29], s[70:71], 1, v[4:5]
	global_store_dword v[24:25], v8, off sc1
	v_cvt_pk_bf16_f32 v8, v6, v7
	s_waitcnt vmcnt(31)
	v_pk_fma_f32 v[6:7], v[0:1], v[6:7], v[52:53]
	global_store_dword v[28:29], v8, off sc1
	v_cvt_pk_bf16_f32 v10, v6, v7
	v_lshl_add_u64 v[8:9], s[50:51], 1, v[4:5]
	s_waitcnt vmcnt(31)
	v_pk_fma_f32 v[6:7], v[0:1], v[6:7], v[54:55]
	global_store_dword v[8:9], v10, off sc1
	v_lshl_add_u64 v[8:9], s[6:7], 1, v[4:5]
	v_cvt_pk_bf16_f32 v26, v6, v7
	s_waitcnt vmcnt(31)
	v_pk_fma_f32 v[6:7], v[0:1], v[6:7], v[56:57]
	v_lshl_add_u64 v[10:11], s[28:29], 1, v[4:5]
	global_store_dword v[8:9], v26, off sc1
	v_cvt_pk_bf16_f32 v8, v6, v7
	s_waitcnt vmcnt(31)
	v_pk_fma_f32 v[6:7], v[0:1], v[6:7], v[58:59]
	v_lshl_add_u64 v[12:13], s[30:31], 1, v[4:5]
	global_store_dword v[10:11], v8, off sc1
	v_cvt_pk_bf16_f32 v8, v6, v7
	s_waitcnt vmcnt(31)
	v_pk_fma_f32 v[6:7], v[0:1], v[6:7], v[60:61]
	v_lshl_add_u64 v[14:15], s[34:35], 1, v[4:5]
	global_store_dword v[12:13], v8, off sc1
	v_cvt_pk_bf16_f32 v8, v6, v7
	s_waitcnt vmcnt(31)
	v_pk_fma_f32 v[6:7], v[0:1], v[6:7], v[62:63]
	v_lshl_add_u64 v[16:17], s[40:41], 1, v[4:5]
	global_store_dword v[14:15], v8, off sc1
	v_cvt_pk_bf16_f32 v8, v6, v7
	s_waitcnt vmcnt(31)
	v_pk_fma_f32 v[6:7], v[0:1], v[6:7], v[64:65]
	v_lshl_add_u64 v[18:19], s[42:43], 1, v[4:5]
	global_store_dword v[16:17], v8, off sc1
	v_cvt_pk_bf16_f32 v8, v6, v7
	s_waitcnt vmcnt(31)
	v_pk_fma_f32 v[6:7], v[0:1], v[6:7], v[66:67]
	v_lshl_add_u64 v[20:21], s[44:45], 1, v[4:5]
	global_store_dword v[18:19], v8, off sc1
	v_cvt_pk_bf16_f32 v8, v6, v7
	s_waitcnt vmcnt(31)
	v_pk_fma_f32 v[6:7], v[0:1], v[6:7], v[68:69]
	v_lshl_add_u64 v[22:23], s[46:47], 1, v[4:5]
	global_store_dword v[20:21], v8, off sc1
	v_cvt_pk_bf16_f32 v8, v6, v7
	s_waitcnt vmcnt(31)
	v_pk_fma_f32 v[6:7], v[0:1], v[6:7], v[70:71]
	v_lshl_add_u64 v[24:25], s[48:49], 1, v[4:5]
	global_store_dword v[22:23], v8, off sc1
	v_cvt_pk_bf16_f32 v8, v6, v7
	s_waitcnt vmcnt(31)
	v_pk_fma_f32 v[6:7], v[0:1], v[6:7], v[72:73]
	global_store_dword v[24:25], v8, off sc1
	v_cvt_pk_bf16_f32 v10, v6, v7
	v_lshl_add_u64 v[8:9], s[4:5], 1, v[4:5]
	s_waitcnt vmcnt(31)
	v_pk_fma_f32 v[6:7], v[0:1], v[6:7], v[74:75]
	s_mov_b32 s82, 0x80000
	s_mov_b64 s[4:5], 0
	global_store_dword v[8:9], v10, off sc1
	s_cbranch_vccz .LBB0_1377
	v_readlane_b32 s0, v252, 58
	s_nop 1
	v_add_u32_e32 v46, s0, v46
	s_mov_b32 s0, 0xffff
	v_cmp_lt_i32_e32 vcc, s0, v46
	s_or_b64 s[38:39], vcc, s[38:39]
	s_andn2_b64 exec, exec, s[38:39]
	s_cbranch_execnz .LBB0_1376

; __device__ __forceinline__ void m2_scans(const Args& a, int l, int tid, int G) {
;     ...
;         for (int nb = 0; nb < 128; nb += 32) {
;             float av[32], hv[32];
; #pragma unroll
;             for (int j = 0; j < 32; ++j) { const size_t o = (size_t)(b * 128 + nb + j) * 256 + ch; av[j] = AE[o]; hv[j] = HE[o]; }
; #pragma unroll
;             for (int j = 0; j < 32; ++j) { const size_t o = (size_t)(b * 128 + nb + j) * 256 + ch; HE[o] = hcar; hcar = fmaf(av[j], hcar, hv[j]); }
.LBB0_1382:
	v_add_co_u32_e32 v4, vcc, 0xfffb9000, v0
	s_mov_b32 s1, 0xfffba000
	s_nop 0
	v_addc_co_u32_e32 v5, vcc, -1, v1, vcc
	global_load_dword v9, v[4:5], off offset:-3072
	v_add_co_u32_e32 v2, vcc, 0xffff9000, v0
	s_add_i32 s0, s0, 32
	s_nop 0
	v_addc_co_u32_e32 v3, vcc, -1, v1, vcc
	v_add_co_u32_e32 v6, vcc, s1, v0
	global_load_dword v20, v[2:3], off offset:-3072
	global_load_dword v21, v[4:5], off offset:-2048
	global_load_dword v22, v[2:3], off offset:-2048
	global_load_dword v23, v[4:5], off offset:-1024
	global_load_dword v24, v[2:3], off offset:-1024
	global_load_dword v25, v[4:5], off
	global_load_dword v26, v[2:3], off
	v_addc_co_u32_e32 v7, vcc, -1, v1, vcc
	global_load_dword v27, v[6:7], off offset:-3072
	v_add_co_u32_e32 v4, vcc, 0xffffa000, v0
	s_movk_i32 s1, 0xc000
	s_nop 0
	v_addc_co_u32_e32 v5, vcc, -1, v1, vcc
	v_add_co_u32_e32 v10, vcc, 0xfffbb000, v0
	global_load_dword v28, v[4:5], off offset:-3072
	global_load_dword v29, v[6:7], off offset:-2048
	global_load_dword v30, v[4:5], off offset:-2048
	global_load_dword v31, v[6:7], off offset:-1024
	global_load_dword v32, v[4:5], off offset:-1024
	global_load_dword v33, v[6:7], off
	global_load_dword v34, v[4:5], off
	v_addc_co_u32_e32 v11, vcc, -1, v1, vcc
	global_load_dword v35, v[10:11], off offset:-3072
	v_add_co_u32_e32 v6, vcc, 0xffffb000, v0
	s_mov_b64 s[24:25], 0x8000
	s_nop 0
	v_addc_co_u32_e32 v7, vcc, -1, v1, vcc
	global_load_dword v36, v[6:7], off offset:-3072
	global_load_dword v37, v[10:11], off offset:-2048
	global_load_dword v38, v[6:7], off offset:-2048
	global_load_dword v39, v[10:11], off offset:-1024
	global_load_dword v40, v[6:7], off offset:-1024
	global_load_dword v41, v[10:11], off
	global_load_dword v42, v[6:7], off
	v_add_co_u32_e32 v10, vcc, 0xfffbc000, v0
	s_cmpk_lt_u32 s0, 0x60
	s_nop 0
	v_addc_co_u32_e32 v11, vcc, -1, v1, vcc
	global_load_dword v43, v[10:11], off offset:-3072
	v_add_co_u32_e32 v12, vcc, s1, v0
	s_movk_i32 s1, 0xe000
	s_nop 0
	v_addc_co_u32_e32 v13, vcc, -1, v1, vcc
	global_load_dword v44, v[12:13], off offset:-3072
	global_load_dword v45, v[10:11], off offset:-2048
	global_load_dword v46, v[12:13], off offset:-2048
	global_load_dword v47, v[10:11], off offset:-1024
	global_load_dword v48, v[12:13], off offset:-1024
	global_load_dword v49, v[10:11], off
	global_load_dword v50, v[12:13], off
	v_add_co_u32_e32 v10, vcc, 0xfffbd000, v0
	s_waitcnt vmcnt(30)
	v_fmac_f32_e32 v20, v9, v8
	v_addc_co_u32_e32 v11, vcc, -1, v1, vcc
	global_load_dword v51, v[10:11], off offset:-3072
	v_add_co_u32_e32 v14, vcc, 0xffffd000, v0
	s_waitcnt vmcnt(29)
	v_fmac_f32_e32 v22, v21, v20
	v_addc_co_u32_e32 v15, vcc, -1, v1, vcc
	global_load_dword v52, v[14:15], off offset:-3072
	global_load_dword v53, v[10:11], off offset:-2048
	global_load_dword v54, v[14:15], off offset:-2048
	global_load_dword v55, v[10:11], off offset:-1024
	global_load_dword v56, v[14:15], off offset:-1024
	global_load_dword v57, v[10:11], off
	global_load_dword v58, v[14:15], off
	v_add_co_u32_e32 v10, vcc, 0xfffbe000, v0
	s_waitcnt vmcnt(34)
	v_fmac_f32_e32 v24, v23, v22
	v_addc_co_u32_e32 v11, vcc, -1, v1, vcc
	global_load_dword v59, v[10:11], off offset:-3072
	v_add_co_u32_e32 v16, vcc, s1, v0
	s_waitcnt vmcnt(33)
	v_fmac_f32_e32 v26, v25, v24
	v_addc_co_u32_e32 v17, vcc, -1, v1, vcc
	global_load_dword v60, v[16:17], off offset:-3072
	global_load_dword v61, v[10:11], off offset:-2048
	global_load_dword v62, v[16:17], off offset:-2048
	global_load_dword v63, v[10:11], off offset:-1024
	global_load_dword v64, v[16:17], off offset:-1024
	global_load_dword v65, v[10:11], off
	global_load_dword v66, v[16:17], off
	v_add_co_u32_e32 v10, vcc, 0xfffbf000, v0
	s_waitcnt vmcnt(38)
	v_fmac_f32_e32 v28, v27, v26
	v_addc_co_u32_e32 v11, vcc, -1, v1, vcc
	global_load_dword v67, v[10:11], off offset:-3072
	v_add_co_u32_e32 v18, vcc, 0xfffff000, v0
	s_waitcnt vmcnt(37)
; __device__ __forceinline__ void m2_scans(const Args& a, int l, int tid, int G) {
;     ...
;             for (int j = 0; j < 32; ++j) { const size_t o = (size_t)(b * 128 + nb + j) * 256 + ch; av[j] = AE[o]; hv[j] = HE[o]; }
; #pragma unroll
;             for (int j = 0; j < 32; ++j) { const size_t o = (size_t)(b * 128 + nb + j) * 256 + ch; HE[o] = hcar; hcar = fmaf(av[j], hcar, hv[j]); }
;         }
	v_fmac_f32_e32 v30, v29, v28
	v_addc_co_u32_e32 v19, vcc, -1, v1, vcc
	global_load_dword v68, v[18:19], off offset:-3072
	global_load_dword v69, v[10:11], off offset:-2048
	global_load_dword v70, v[18:19], off offset:-2048
	global_load_dword v71, v[10:11], off offset:-1024
	global_load_dword v72, v[18:19], off offset:-1024
	global_load_dword v73, v[10:11], off
	global_load_dword v74, v[0:1], off offset:-4096
	v_add_co_u32_e32 v10, vcc, 0xfffc0000, v0
	s_waitcnt vmcnt(42)
	v_fmac_f32_e32 v32, v31, v30
	v_addc_co_u32_e32 v11, vcc, -1, v1, vcc
	global_load_dword v75, v[10:11], off offset:-3072
	global_load_dword v76, v[0:1], off offset:-3072
	global_load_dword v77, v[10:11], off offset:-2048
	global_load_dword v78, v[0:1], off offset:-2048
	global_load_dword v79, v[10:11], off offset:-1024
	global_load_dword v80, v[0:1], off offset:-1024
	s_nop 0
	global_load_dword v10, v[10:11], off
	s_nop 0
	global_load_dword v11, v[0:1], off
	s_waitcnt vmcnt(48)
	v_fmac_f32_e32 v34, v33, v32
	s_waitcnt vmcnt(46)
	v_fmac_f32_e32 v36, v35, v34
	s_waitcnt vmcnt(44)
	v_fmac_f32_e32 v38, v37, v36
	s_waitcnt vmcnt(42)
	v_fmac_f32_e32 v40, v39, v38
	s_waitcnt vmcnt(40)
	v_fmac_f32_e32 v42, v41, v40
	s_waitcnt vmcnt(38)
	v_fmac_f32_e32 v44, v43, v42
	s_waitcnt vmcnt(36)
	v_fmac_f32_e32 v46, v45, v44
	s_waitcnt vmcnt(34)
	v_fmac_f32_e32 v48, v47, v46
	s_waitcnt vmcnt(32)
	v_fmac_f32_e32 v50, v49, v48
	global_store_dword v[2:3], v8, off offset:-3072 sc1
	global_store_dword v[2:3], v20, off offset:-2048 sc1
	global_store_dword v[2:3], v22, off offset:-1024 sc1
	global_store_dword v[2:3], v24, off sc1
	global_store_dword v[4:5], v26, off offset:-3072 sc1
	global_store_dword v[4:5], v28, off offset:-2048 sc1
	global_store_dword v[4:5], v30, off offset:-1024 sc1
	global_store_dword v[4:5], v32, off sc1
	global_store_dword v[6:7], v34, off offset:-3072 sc1
	global_store_dword v[6:7], v36, off offset:-2048 sc1
	global_store_dword v[6:7], v38, off offset:-1024 sc1
	global_store_dword v[6:7], v40, off sc1
	global_store_dword v[12:13], v42, off offset:-3072 sc1
	global_store_dword v[12:13], v44, off offset:-2048 sc1
	global_store_dword v[12:13], v46, off offset:-1024 sc1
	global_store_dword v[12:13], v48, off sc1
	global_store_dword v[14:15], v50, off offset:-3072 sc1
	s_waitcnt vmcnt(47)
	v_fmac_f32_e32 v52, v51, v50
	global_store_dword v[14:15], v52, off offset:-2048 sc1
	s_waitcnt vmcnt(46)
	v_fmac_f32_e32 v54, v53, v52
	global_store_dword v[14:15], v54, off offset:-1024 sc1
	s_waitcnt vmcnt(45)
	v_fmac_f32_e32 v56, v55, v54
	global_store_dword v[14:15], v56, off sc1
	s_waitcnt vmcnt(44)
	v_fmac_f32_e32 v58, v57, v56
	global_store_dword v[16:17], v58, off offset:-3072 sc1
	s_waitcnt vmcnt(43)
	v_fmac_f32_e32 v60, v59, v58
	global_store_dword v[16:17], v60, off offset:-2048 sc1
	s_waitcnt vmcnt(42)
	v_fmac_f32_e32 v62, v61, v60
	global_store_dword v[16:17], v62, off offset:-1024 sc1
	s_waitcnt vmcnt(41)
	v_fmac_f32_e32 v64, v63, v62
	global_store_dword v[16:17], v64, off sc1
	s_waitcnt vmcnt(40)
	v_fmac_f32_e32 v66, v65, v64
	global_store_dword v[18:19], v66, off offset:-3072 sc1
	s_waitcnt vmcnt(39)
	v_fmac_f32_e32 v68, v67, v66
	global_store_dword v[18:19], v68, off offset:-2048 sc1
	s_waitcnt vmcnt(38)
	v_fmac_f32_e32 v70, v69, v68
	global_store_dword v[18:19], v70, off offset:-1024 sc1
	s_waitcnt vmcnt(37)
	v_fmac_f32_e32 v72, v71, v70
	global_store_dword v[0:1], v72, off offset:-4096 sc1
	s_waitcnt vmcnt(36)
	v_fmac_f32_e32 v74, v73, v72
	s_waitcnt vmcnt(34)
	v_fmac_f32_e32 v76, v75, v74
	s_waitcnt vmcnt(32)
	v_fmac_f32_e32 v78, v77, v76
	global_store_dword v[0:1], v74, off offset:-3072 sc1
	s_waitcnt vmcnt(31)
	v_fmac_f32_e32 v80, v79, v78
	global_store_dword v[0:1], v76, off offset:-2048 sc1
	s_waitcnt vmcnt(30)
	v_fmac_f32_e32 v11, v10, v80
	global_store_dword v[0:1], v78, off offset:-1024 sc1
	global_store_dword v[0:1], v80, off sc1
	v_lshl_add_u64 v[0:1], v[0:1], 0, s[24:25]
	v_mov_b32_e32 v8, v11
	s_cbranch_scc1 .LBB0_1382

; __device__ __forceinline__ void m2_scans(const Args& a, int l, int tid, int G) {
;     ...
;         for (int nb = 0; nb < 128; nb += 32) {
;             float er[32], ei[32];
; #pragma unroll
;             for (int j = 0; j < 32; ++j) { const size_t o = ((size_t)((b * 128 + nb + j) * 16 + g) * 2) * 64 + p; er[j] = E[o]; ei[j] = E[o + 64]; }
.LBB0_1386:
	v_add_u32_e32 v14, 0xfffffe10, v4
	v_add_u32_e32 v16, 0xfffffe20, v4
	v_add_u32_e32 v18, 0xfffffe30, v4
	v_add_u32_e32 v20, 0xfffffe40, v4
	v_add_u32_e32 v22, 0xfffffe50, v4
	v_add_u32_e32 v24, 0xfffffe60, v4
	v_add_u32_e32 v26, 0xfffffe70, v4
	v_add_u32_e32 v28, 0xfffffe80, v4
	v_add_u32_e32 v30, 0xfffffe90, v4
	v_add_u32_e32 v32, 0xfffffea0, v4
	v_add_u32_e32 v34, 0xfffffeb0, v4
	v_add_u32_e32 v36, 0xfffffec0, v4
	v_add_u32_e32 v38, 0xfffffed0, v4
	v_add_u32_e32 v40, 0xfffffee0, v4
	v_add_u32_e32 v42, 0xfffffef0, v4
	v_add_u32_e32 v44, 0xffffff00, v4
	v_add_u32_e32 v46, 0xffffff10, v4
	v_add_u32_e32 v48, 0xffffff20, v4
	v_add_u32_e32 v50, 0xffffff30, v4
	v_add_u32_e32 v52, 0xffffff40, v4
	v_add_u32_e32 v54, 0xffffff50, v4
	v_add_u32_e32 v56, 0xffffff60, v4
	v_add_u32_e32 v58, 0xffffff70, v4
	v_add_u32_e32 v60, 0xffffff80, v4
	v_add_u32_e32 v62, 0xffffff90, v4
	v_add_u32_e32 v64, 0xffffffa0, v4
	v_add_u32_e32 v66, 0xffffffb0, v4
	v_subrev_u32_e32 v68, 64, v4
	v_subrev_u32_e32 v70, 48, v4
	v_subrev_u32_e32 v72, 32, v4
	v_add_u32_e32 v74, -16, v4
	v_ashrrev_i32_e32 v15, 31, v14
	v_ashrrev_i32_e32 v5, 31, v4
	v_pk_mul_f32 v[76:77], v[2:3], v[12:13]
	v_ashrrev_i32_e32 v17, 31, v16
	v_ashrrev_i32_e32 v19, 31, v18
	v_ashrrev_i32_e32 v21, 31, v20
	v_ashrrev_i32_e32 v23, 31, v22
	v_ashrrev_i32_e32 v25, 31, v24
	v_ashrrev_i32_e32 v27, 31, v26
	v_ashrrev_i32_e32 v29, 31, v28
	v_ashrrev_i32_e32 v31, 31, v30
	v_ashrrev_i32_e32 v33, 31, v32
	v_ashrrev_i32_e32 v35, 31, v34
	v_ashrrev_i32_e32 v37, 31, v36
	v_ashrrev_i32_e32 v39, 31, v38
	v_ashrrev_i32_e32 v41, 31, v40
	v_ashrrev_i32_e32 v43, 31, v42
	v_ashrrev_i32_e32 v45, 31, v44
	v_ashrrev_i32_e32 v47, 31, v46
	v_ashrrev_i32_e32 v49, 31, v48
	v_ashrrev_i32_e32 v51, 31, v50
	v_ashrrev_i32_e32 v53, 31, v52
	v_ashrrev_i32_e32 v55, 31, v54
	v_ashrrev_i32_e32 v57, 31, v56
	v_ashrrev_i32_e32 v59, 31, v58
	v_ashrrev_i32_e32 v61, 31, v60
	v_ashrrev_i32_e32 v63, 31, v62
	v_ashrrev_i32_e32 v65, 31, v64
	v_ashrrev_i32_e32 v67, 31, v66
	v_ashrrev_i32_e32 v69, 31, v68
	v_ashrrev_i32_e32 v71, 31, v70
	v_ashrrev_i32_e32 v73, 31, v72
	v_ashrrev_i32_e32 v75, 31, v74
	v_lshlrev_b64 v[80:81], 9, v[14:15]
	v_lshlrev_b64 v[78:79], 9, v[4:5]
	v_pk_fma_f32 v[100:101], v[0:1], v[12:13], v[76:77] op_sel:[0,0,1] op_sel_hi:[1,1,0] neg_lo:[0,0,1] neg_hi:[0,0,1]
	v_pk_fma_f32 v[76:77], v[0:1], v[12:13], v[76:77] op_sel:[0,0,1] op_sel_hi:[1,1,0]
	v_lshlrev_b64 v[16:17], 9, v[16:17]
	v_lshlrev_b64 v[18:19], 9, v[18:19]
	v_lshlrev_b64 v[20:21], 9, v[20:21]
	v_lshlrev_b64 v[22:23], 9, v[22:23]
	v_lshlrev_b64 v[24:25], 9, v[24:25]
	v_lshlrev_b64 v[26:27], 9, v[26:27]
	v_lshlrev_b64 v[28:29], 9, v[28:29]
	v_lshlrev_b64 v[30:31], 9, v[30:31]
	v_lshlrev_b64 v[32:33], 9, v[32:33]
	v_lshlrev_b64 v[34:35], 9, v[34:35]
	v_lshlrev_b64 v[36:37], 9, v[36:37]
	v_lshlrev_b64 v[38:39], 9, v[38:39]
	v_lshlrev_b64 v[40:41], 9, v[40:41]
	v_lshlrev_b64 v[42:43], 9, v[42:43]
	v_lshlrev_b64 v[44:45], 9, v[44:45]
	v_lshlrev_b64 v[46:47], 9, v[46:47]
	v_lshlrev_b64 v[48:49], 9, v[48:49]
	v_lshlrev_b64 v[50:51], 9, v[50:51]
	v_lshlrev_b64 v[82:83], 9, v[52:53]
	v_lshlrev_b64 v[54:55], 9, v[54:55]
	v_lshlrev_b64 v[86:87], 9, v[56:57]
	v_lshlrev_b64 v[58:59], 9, v[58:59]
	v_lshlrev_b64 v[88:89], 9, v[60:61]
	v_lshlrev_b64 v[62:63], 9, v[62:63]
	v_lshlrev_b64 v[64:65], 9, v[64:65]
	v_lshlrev_b64 v[92:93], 9, v[66:67]
	v_lshlrev_b64 v[68:69], 9, v[68:69]
	v_lshlrev_b64 v[96:97], 9, v[70:71]
	v_lshlrev_b64 v[72:73], 9, v[72:73]
	v_lshlrev_b64 v[102:103], 9, v[74:75]
	v_lshl_add_u64 v[108:109], v[6:7], 0, v[80:81]
	v_lshl_add_u64 v[14:15], v[6:7], 0, v[78:79]
	v_mov_b32_e32 v101, v77
	v_lshl_add_u64 v[110:111], v[6:7], 0, v[16:17]
	v_lshl_add_u64 v[112:113], v[6:7], 0, v[18:19]
	v_lshl_add_u64 v[114:115], v[6:7], 0, v[20:21]
	v_lshl_add_u64 v[116:117], v[6:7], 0, v[22:23]
	v_lshl_add_u64 v[118:119], v[6:7], 0, v[24:25]
	v_lshl_add_u64 v[104:105], v[6:7], 0, v[26:27]
	v_lshl_add_u64 v[98:99], v[6:7], 0, v[28:29]
	v_lshl_add_u64 v[94:95], v[6:7], 0, v[30:31]
	v_lshl_add_u64 v[90:91], v[6:7], 0, v[32:33]
	v_lshl_add_u64 v[84:85], v[6:7], 0, v[34:35]
	v_lshl_add_u64 v[80:81], v[6:7], 0, v[36:37]
	v_lshl_add_u64 v[74:75], v[6:7], 0, v[38:39]
	v_lshl_add_u64 v[70:71], v[6:7], 0, v[40:41]
	v_lshl_add_u64 v[66:67], v[6:7], 0, v[42:43]
	v_lshl_add_u64 v[60:61], v[6:7], 0, v[44:45]
	v_lshl_add_u64 v[56:57], v[6:7], 0, v[46:47]
	v_lshl_add_u64 v[52:53], v[6:7], 0, v[48:49]
	v_lshl_add_u64 v[48:49], v[6:7], 0, v[50:51]
	v_lshl_add_u64 v[44:45], v[6:7], 0, v[82:83]
	v_lshl_add_u64 v[38:39], v[6:7], 0, v[54:55]
	v_lshl_add_u64 v[34:35], v[6:7], 0, v[86:87]
	v_lshl_add_u64 v[32:33], v[6:7], 0, v[58:59]
	v_lshl_add_u64 v[30:31], v[6:7], 0, v[88:89]
	v_lshl_add_u64 v[28:29], v[6:7], 0, v[62:63]
	v_lshl_add_u64 v[26:27], v[6:7], 0, v[64:65]
	v_lshl_add_u64 v[24:25], v[6:7], 0, v[92:93]
	v_lshl_add_u64 v[22:23], v[6:7], 0, v[68:69]
	v_lshl_add_u64 v[20:21], v[6:7], 0, v[96:97]
	v_lshl_add_u64 v[18:19], v[6:7], 0, v[72:73]
	v_lshl_add_u64 v[16:17], v[6:7], 0, v[102:103]
	global_load_dword v120, v[108:109], off
	global_load_dword v121, v[108:109], off offset:256
	global_load_dword v122, v[110:111], off
	global_load_dword v123, v[110:111], off offset:256
	global_load_dword v124, v[112:113], off
	global_load_dword v125, v[112:113], off offset:256
	global_load_dword v126, v[114:115], off
	global_load_dword v127, v[114:115], off offset:256
	global_load_dword v128, v[116:117], off
	global_load_dword v129, v[116:117], off offset:256
	global_load_dword v130, v[118:119], off
	global_load_dword v131, v[118:119], off offset:256
	global_load_dword v132, v[104:105], off
; __device__ __forceinline__ void m2_scans(const Args& a, int l, int tid, int G) {
;     ...
;             for (int j = 0; j < 32; ++j) { const size_t o = ((size_t)((b * 128 + nb + j) * 16 + g) * 2) * 64 + p; er[j] = E[o]; ei[j] = E[o + 64]; }
; #pragma unroll
;             for (int j = 0; j < 32; ++j) { const size_t o = ((size_t)((b * 128 + nb + j) * 16 + g) * 2) * 64 + p; E[o] = sre; E[o + 64] = sim;
;                 const float nre = cr * sre - ci * sim + er[j], nim = cr * sim + ci * sre + ei[j]; sre = nre; sim = nim; }
	global_load_dword v133, v[104:105], off offset:256
	global_load_dword v134, v[98:99], off
	global_load_dword v135, v[98:99], off offset:256
	global_load_dword v136, v[94:95], off
	global_load_dword v137, v[94:95], off offset:256
	global_load_dword v138, v[90:91], off
	global_load_dword v139, v[90:91], off offset:256
	global_load_dword v141, v[84:85], off
	global_load_dword v140, v[84:85], off offset:256
	global_load_dword v143, v[80:81], off
	global_load_dword v142, v[80:81], off offset:256
	global_load_dword v107, v[74:75], off
	global_load_dword v106, v[74:75], off offset:256
	global_load_dword v103, v[70:71], off
	global_load_dword v102, v[70:71], off offset:256
	global_load_dword v97, v[66:67], off
	global_load_dword v96, v[66:67], off offset:256
	global_load_dword v93, v[60:61], off
	global_load_dword v92, v[60:61], off offset:256
	global_load_dword v89, v[56:57], off
	global_load_dword v88, v[56:57], off offset:256
	global_load_dword v87, v[52:53], off
	global_load_dword v86, v[52:53], off offset:256
	global_load_dword v83, v[48:49], off
	global_load_dword v82, v[48:49], off offset:256
	global_load_dword v77, v[44:45], off
	global_load_dword v76, v[44:45], off offset:256
	global_load_dword v73, v[38:39], off
	global_load_dword v72, v[38:39], off offset:256
	global_load_dword v68, v[34:35], off
	global_load_dword v69, v[34:35], off offset:256
	global_load_dword v64, v[32:33], off
	global_load_dword v65, v[32:33], off offset:256
	global_load_dword v62, v[30:31], off
	global_load_dword v63, v[30:31], off offset:256
	global_load_dword v58, v[28:29], off
	global_load_dword v59, v[28:29], off offset:256
	global_load_dword v54, v[26:27], off
	global_load_dword v55, v[26:27], off offset:256
	global_load_dword v50, v[24:25], off
	global_load_dword v51, v[24:25], off offset:256
	global_load_dword v46, v[22:23], off
	global_load_dword v47, v[22:23], off offset:256
	global_load_dword v42, v[20:21], off
	global_load_dword v43, v[20:21], off offset:256
	global_load_dword v40, v[18:19], off
	global_load_dword v41, v[18:19], off offset:256
	global_load_dword v36, v[16:17], off
	global_load_dword v37, v[16:17], off offset:256
	global_load_dword v78, v[14:15], off
	global_load_dword v79, v[14:15], off offset:256
	s_nop 0
	global_store_dword v[108:109], v12, off sc1
	global_store_dword v[108:109], v13, off offset:256 sc1
	s_add_i32 s0, s0, 32
	v_add_u32_e32 v4, 0x200, v4
	s_cmpk_gt_u32 s0, 0x5f
	s_waitcnt vmcnt(62)
	v_pk_add_f32 v[12:13], v[100:101], v[120:121]
	s_nop 0
	v_pk_mul_f32 v[100:101], v[2:3], v[12:13]
	global_store_dword v[110:111], v12, off sc1
	global_store_dword v[110:111], v13, off offset:256 sc1
	v_pk_fma_f32 v[108:109], v[0:1], v[12:13], v[100:101] op_sel:[0,0,1] op_sel_hi:[1,1,0] neg_lo:[0,0,1] neg_hi:[0,0,1]
	v_pk_fma_f32 v[12:13], v[0:1], v[12:13], v[100:101] op_sel:[0,0,1] op_sel_hi:[1,1,0]
	s_nop 0
	v_mov_b32_e32 v109, v13
	v_pk_add_f32 v[12:13], v[122:123], v[108:109]
	global_store_dword v[112:113], v12, off sc1
	global_store_dword v[112:113], v13, off offset:256 sc1
	v_pk_mul_f32 v[100:101], v[2:3], v[12:13]
	s_nop 0
	v_pk_fma_f32 v[108:109], v[0:1], v[12:13], v[100:101] op_sel:[0,0,1] op_sel_hi:[1,1,0] neg_lo:[0,0,1] neg_hi:[0,0,1]
	v_pk_fma_f32 v[12:13], v[0:1], v[12:13], v[100:101] op_sel:[0,0,1] op_sel_hi:[1,1,0]
	s_nop 0
	v_mov_b32_e32 v109, v13
	s_waitcnt vmcnt(62)
	v_pk_add_f32 v[12:13], v[124:125], v[108:109]
	global_store_dword v[114:115], v12, off sc1
	global_store_dword v[114:115], v13, off offset:256 sc1
	v_pk_mul_f32 v[100:101], v[2:3], v[12:13]
	s_nop 0
	v_pk_fma_f32 v[108:109], v[0:1], v[12:13], v[100:101] op_sel:[0,0,1] op_sel_hi:[1,1,0] neg_lo:[0,0,1] neg_hi:[0,0,1]
	v_pk_fma_f32 v[12:13], v[0:1], v[12:13], v[100:101] op_sel:[0,0,1] op_sel_hi:[1,1,0]
	s_nop 0
	v_mov_b32_e32 v109, v13
	v_pk_add_f32 v[12:13], v[126:127], v[108:109]
	global_store_dword v[116:117], v12, off sc1
	global_store_dword v[116:117], v13, off offset:256 sc1
	v_pk_mul_f32 v[100:101], v[2:3], v[12:13]
	s_nop 0
	v_pk_fma_f32 v[108:109], v[0:1], v[12:13], v[100:101] op_sel:[0,0,1] op_sel_hi:[1,1,0] neg_lo:[0,0,1] neg_hi:[0,0,1]
	v_pk_fma_f32 v[12:13], v[0:1], v[12:13], v[100:101] op_sel:[0,0,1] op_sel_hi:[1,1,0]
	s_nop 0
	v_mov_b32_e32 v109, v13
	s_waitcnt vmcnt(62)
	v_pk_add_f32 v[12:13], v[128:129], v[108:109]
	global_store_dword v[118:119], v12, off sc1
	global_store_dword v[118:119], v13, off offset:256 sc1
	v_pk_mul_f32 v[100:101], v[2:3], v[12:13]
	s_nop 0
	v_pk_fma_f32 v[108:109], v[0:1], v[12:13], v[100:101] op_sel:[0,0,1] op_sel_hi:[1,1,0] neg_lo:[0,0,1] neg_hi:[0,0,1]
	v_pk_fma_f32 v[12:13], v[0:1], v[12:13], v[100:101] op_sel:[0,0,1] op_sel_hi:[1,1,0]
	s_nop 0
	v_mov_b32_e32 v109, v13
	v_pk_add_f32 v[12:13], v[130:131], v[108:109]
	global_store_dword v[104:105], v12, off sc1
	global_store_dword v[104:105], v13, off offset:256 sc1
	v_pk_mul_f32 v[100:101], v[2:3], v[12:13]
	s_nop 0
	v_pk_fma_f32 v[104:105], v[0:1], v[12:13], v[100:101] op_sel:[0,0,1] op_sel_hi:[1,1,0] neg_lo:[0,0,1] neg_hi:[0,0,1]
	v_pk_fma_f32 v[12:13], v[0:1], v[12:13], v[100:101] op_sel:[0,0,1] op_sel_hi:[1,1,0]
	s_nop 0
	v_mov_b32_e32 v105, v13
	s_waitcnt vmcnt(62)
	v_pk_add_f32 v[12:13], v[132:133], v[104:105]
	global_store_dword v[98:99], v12, off sc1
	global_store_dword v[98:99], v13, off offset:256 sc1
	v_pk_mul_f32 v[98:99], v[2:3], v[12:13]
	s_nop 0
	v_pk_fma_f32 v[100:101], v[0:1], v[12:13], v[98:99] op_sel:[0,0,1] op_sel_hi:[1,1,0] neg_lo:[0,0,1] neg_hi:[0,0,1]
	v_pk_fma_f32 v[12:13], v[0:1], v[12:13], v[98:99] op_sel:[0,0,1] op_sel_hi:[1,1,0]
	s_nop 0
	v_mov_b32_e32 v101, v13
	v_pk_add_f32 v[12:13], v[134:135], v[100:101]
	global_store_dword v[94:95], v12, off sc1
	global_store_dword v[94:95], v13, off offset:256 sc1
	v_pk_mul_f32 v[94:95], v[2:3], v[12:13]
	s_nop 0
	v_pk_fma_f32 v[98:99], v[0:1], v[12:13], v[94:95] op_sel:[0,0,1] op_sel_hi:[1,1,0] neg_lo:[0,0,1] neg_hi:[0,0,1]
	v_pk_fma_f32 v[12:13], v[0:1], v[12:13], v[94:95] op_sel:[0,0,1] op_sel_hi:[1,1,0]
	s_nop 0
	v_mov_b32_e32 v99, v13
	s_waitcnt vmcnt(62)
; __device__ __forceinline__ void m2_scans(const Args& a, int l, int tid, int G) {
;     ...
;             for (int j = 0; j < 32; ++j) { const size_t o = ((size_t)((b * 128 + nb + j) * 16 + g) * 2) * 64 + p; er[j] = E[o]; ei[j] = E[o + 64]; }
; #pragma unroll
;             for (int j = 0; j < 32; ++j) { const size_t o = ((size_t)((b * 128 + nb + j) * 16 + g) * 2) * 64 + p; E[o] = sre; E[o + 64] = sim;
;                 const float nre = cr * sre - ci * sim + er[j], nim = cr * sim + ci * sre + ei[j]; sre = nre; sim = nim; }
	v_pk_add_f32 v[12:13], v[136:137], v[98:99]
	global_store_dword v[90:91], v12, off sc1
	global_store_dword v[90:91], v13, off offset:256 sc1
	v_pk_mul_f32 v[90:91], v[2:3], v[12:13]
	s_nop 0
	v_pk_fma_f32 v[94:95], v[0:1], v[12:13], v[90:91] op_sel:[0,0,1] op_sel_hi:[1,1,0] neg_lo:[0,0,1] neg_hi:[0,0,1]
	v_pk_fma_f32 v[12:13], v[0:1], v[12:13], v[90:91] op_sel:[0,0,1] op_sel_hi:[1,1,0]
	s_nop 0
	v_mov_b32_e32 v95, v13
	v_pk_add_f32 v[12:13], v[138:139], v[94:95]
	global_store_dword v[84:85], v12, off sc1
	global_store_dword v[84:85], v13, off offset:256 sc1
	v_mul_f32_e32 v84, v8, v12
	v_mul_f32_e32 v90, v11, v13
	v_pk_fma_f32 v[84:85], v[8:9], v[12:13], v[84:85] op_sel_hi:[1,1,0] neg_lo:[1,0,0] neg_hi:[1,0,0]
	v_pk_fma_f32 v[12:13], v[10:11], v[12:13], v[90:91] op_sel_hi:[1,1,0]
	s_nop 0
	v_mov_b32_e32 v13, v85
	s_waitcnt vmcnt(62)
	v_pk_add_f32 v[12:13], v[140:141], v[12:13]
	global_store_dword v[80:81], v13, off sc1
	global_store_dword v[80:81], v12, off offset:256 sc1
	v_pk_mul_f32 v[80:81], v[2:3], v[12:13]
	s_nop 0
	v_pk_fma_f32 v[84:85], v[0:1], v[12:13], v[80:81] op_sel:[0,0,1] op_sel_hi:[1,1,0]
	v_pk_fma_f32 v[12:13], v[0:1], v[12:13], v[80:81] op_sel:[0,0,1] op_sel_hi:[1,1,0] neg_lo:[0,0,1] neg_hi:[0,0,1]
	s_nop 0
	v_mov_b32_e32 v85, v13
	v_pk_add_f32 v[12:13], v[142:143], v[84:85]
	global_store_dword v[74:75], v13, off sc1
	global_store_dword v[74:75], v12, off offset:256 sc1
	v_pk_mul_f32 v[74:75], v[2:3], v[12:13]
	s_nop 0
	v_pk_fma_f32 v[80:81], v[0:1], v[12:13], v[74:75] op_sel:[0,0,1] op_sel_hi:[1,1,0]
	v_pk_fma_f32 v[12:13], v[0:1], v[12:13], v[74:75] op_sel:[0,0,1] op_sel_hi:[1,1,0] neg_lo:[0,0,1] neg_hi:[0,0,1]
	s_nop 0
	v_mov_b32_e32 v81, v13
	s_waitcnt vmcnt(62)
	v_pk_add_f32 v[12:13], v[106:107], v[80:81]
	global_store_dword v[70:71], v13, off sc1
	global_store_dword v[70:71], v12, off offset:256 sc1
	v_pk_mul_f32 v[70:71], v[2:3], v[12:13]
	s_nop 0
	v_pk_fma_f32 v[74:75], v[0:1], v[12:13], v[70:71] op_sel:[0,0,1] op_sel_hi:[1,1,0]
	v_pk_fma_f32 v[12:13], v[0:1], v[12:13], v[70:71] op_sel:[0,0,1] op_sel_hi:[1,1,0] neg_lo:[0,0,1] neg_hi:[0,0,1]
	s_nop 0
	v_mov_b32_e32 v75, v13
	v_pk_add_f32 v[12:13], v[102:103], v[74:75]
	global_store_dword v[66:67], v13, off sc1
	global_store_dword v[66:67], v12, off offset:256 sc1
	v_pk_mul_f32 v[66:67], v[2:3], v[12:13]
	s_nop 0
	v_pk_fma_f32 v[70:71], v[0:1], v[12:13], v[66:67] op_sel:[0,0,1] op_sel_hi:[1,1,0]
	v_pk_fma_f32 v[12:13], v[0:1], v[12:13], v[66:67] op_sel:[0,0,1] op_sel_hi:[1,1,0] neg_lo:[0,0,1] neg_hi:[0,0,1]
	s_nop 0
	v_mov_b32_e32 v71, v13
	s_waitcnt vmcnt(62)
	v_pk_add_f32 v[12:13], v[96:97], v[70:71]
	global_store_dword v[60:61], v13, off sc1
	global_store_dword v[60:61], v12, off offset:256 sc1
	v_pk_mul_f32 v[60:61], v[2:3], v[12:13]
	s_nop 0
	v_pk_fma_f32 v[66:67], v[0:1], v[12:13], v[60:61] op_sel:[0,0,1] op_sel_hi:[1,1,0]
	v_pk_fma_f32 v[12:13], v[0:1], v[12:13], v[60:61] op_sel:[0,0,1] op_sel_hi:[1,1,0] neg_lo:[0,0,1] neg_hi:[0,0,1]
	s_nop 0
	v_mov_b32_e32 v67, v13
	v_pk_add_f32 v[12:13], v[92:93], v[66:67]
	global_store_dword v[56:57], v13, off sc1
	global_store_dword v[56:57], v12, off offset:256 sc1
	v_pk_mul_f32 v[56:57], v[2:3], v[12:13]
	s_nop 0
	v_pk_fma_f32 v[60:61], v[0:1], v[12:13], v[56:57] op_sel:[0,0,1] op_sel_hi:[1,1,0]
	v_pk_fma_f32 v[12:13], v[0:1], v[12:13], v[56:57] op_sel:[0,0,1] op_sel_hi:[1,1,0] neg_lo:[0,0,1] neg_hi:[0,0,1]
	s_nop 0
	v_mov_b32_e32 v61, v13
	s_waitcnt vmcnt(62)
	v_pk_add_f32 v[12:13], v[88:89], v[60:61]
	global_store_dword v[52:53], v13, off sc1
	global_store_dword v[52:53], v12, off offset:256 sc1
	v_pk_mul_f32 v[52:53], v[2:3], v[12:13]
	s_nop 0
	v_pk_fma_f32 v[56:57], v[0:1], v[12:13], v[52:53] op_sel:[0,0,1] op_sel_hi:[1,1,0]
	v_pk_fma_f32 v[12:13], v[0:1], v[12:13], v[52:53] op_sel:[0,0,1] op_sel_hi:[1,1,0] neg_lo:[0,0,1] neg_hi:[0,0,1]
	s_nop 0
	v_mov_b32_e32 v57, v13
	v_pk_add_f32 v[12:13], v[86:87], v[56:57]
	global_store_dword v[48:49], v13, off sc1
	global_store_dword v[48:49], v12, off offset:256 sc1
	v_pk_mul_f32 v[48:49], v[2:3], v[12:13]
	s_nop 0
	v_pk_fma_f32 v[52:53], v[0:1], v[12:13], v[48:49] op_sel:[0,0,1] op_sel_hi:[1,1,0]
	v_pk_fma_f32 v[12:13], v[0:1], v[12:13], v[48:49] op_sel:[0,0,1] op_sel_hi:[1,1,0] neg_lo:[0,0,1] neg_hi:[0,0,1]
	s_nop 0
	v_mov_b32_e32 v53, v13
	s_waitcnt vmcnt(62)
	v_pk_add_f32 v[12:13], v[82:83], v[52:53]
	global_store_dword v[44:45], v13, off sc1
	global_store_dword v[44:45], v12, off offset:256 sc1
	v_pk_mul_f32 v[44:45], v[2:3], v[12:13]
	s_nop 0
	v_pk_fma_f32 v[48:49], v[0:1], v[12:13], v[44:45] op_sel:[0,0,1] op_sel_hi:[1,1,0]
	v_pk_fma_f32 v[12:13], v[0:1], v[12:13], v[44:45] op_sel:[0,0,1] op_sel_hi:[1,1,0] neg_lo:[0,0,1] neg_hi:[0,0,1]
	s_nop 0
	v_mov_b32_e32 v49, v13
	v_pk_add_f32 v[12:13], v[76:77], v[48:49]
	global_store_dword v[38:39], v13, off sc1
	global_store_dword v[38:39], v12, off offset:256 sc1
	v_pk_mul_f32 v[38:39], v[2:3], v[12:13]
	s_nop 0
	v_pk_fma_f32 v[44:45], v[0:1], v[12:13], v[38:39] op_sel:[0,0,1] op_sel_hi:[1,1,0]
	v_pk_fma_f32 v[12:13], v[0:1], v[12:13], v[38:39] op_sel:[0,0,1] op_sel_hi:[1,1,0] neg_lo:[0,0,1] neg_hi:[0,0,1]
	s_nop 0
	v_mov_b32_e32 v45, v13
	s_waitcnt vmcnt(62)
; __device__ __forceinline__ void m2_scans(const Args& a, int l, int tid, int G) {
;     ...
;             for (int j = 0; j < 32; ++j) { const size_t o = ((size_t)((b * 128 + nb + j) * 16 + g) * 2) * 64 + p; er[j] = E[o]; ei[j] = E[o + 64]; }
; #pragma unroll
;             for (int j = 0; j < 32; ++j) { const size_t o = ((size_t)((b * 128 + nb + j) * 16 + g) * 2) * 64 + p; E[o] = sre; E[o + 64] = sim;
;                 const float nre = cr * sre - ci * sim + er[j], nim = cr * sim + ci * sre + ei[j]; sre = nre; sim = nim; }
;         }
	v_pk_add_f32 v[12:13], v[72:73], v[44:45]
	global_store_dword v[34:35], v13, off sc1
	global_store_dword v[34:35], v12, off offset:256 sc1
	v_mul_f32_e32 v34, v11, v13
	v_mul_f32_e32 v38, v8, v12
	v_pk_fma_f32 v[34:35], v[10:11], v[12:13], v[34:35] op_sel_hi:[1,1,0] neg_lo:[1,0,0] neg_hi:[1,0,0]
	v_pk_fma_f32 v[12:13], v[8:9], v[12:13], v[38:39] op_sel_hi:[1,1,0]
	s_nop 0
	v_mov_b32_e32 v35, v13
	v_pk_add_f32 v[12:13], v[68:69], v[34:35]
	global_store_dword v[32:33], v12, off sc1
	global_store_dword v[32:33], v13, off offset:256 sc1
	v_pk_mul_f32 v[32:33], v[2:3], v[12:13]
	s_nop 0
	v_pk_fma_f32 v[34:35], v[0:1], v[12:13], v[32:33] op_sel:[0,0,1] op_sel_hi:[1,1,0] neg_lo:[0,0,1] neg_hi:[0,0,1]
	v_pk_fma_f32 v[12:13], v[0:1], v[12:13], v[32:33] op_sel:[0,0,1] op_sel_hi:[1,1,0]
	s_nop 0
	v_mov_b32_e32 v35, v13
	s_waitcnt vmcnt(62)
	v_pk_add_f32 v[12:13], v[64:65], v[34:35]
	global_store_dword v[30:31], v12, off sc1
	global_store_dword v[30:31], v13, off offset:256 sc1
	v_pk_mul_f32 v[30:31], v[2:3], v[12:13]
	s_nop 0
	v_pk_fma_f32 v[32:33], v[0:1], v[12:13], v[30:31] op_sel:[0,0,1] op_sel_hi:[1,1,0] neg_lo:[0,0,1] neg_hi:[0,0,1]
	v_pk_fma_f32 v[12:13], v[0:1], v[12:13], v[30:31] op_sel:[0,0,1] op_sel_hi:[1,1,0]
	s_nop 0
	v_mov_b32_e32 v33, v13
	v_pk_add_f32 v[12:13], v[62:63], v[32:33]
	global_store_dword v[28:29], v12, off sc1
	global_store_dword v[28:29], v13, off offset:256 sc1
	v_pk_mul_f32 v[28:29], v[2:3], v[12:13]
	s_nop 0
	v_pk_fma_f32 v[30:31], v[0:1], v[12:13], v[28:29] op_sel:[0,0,1] op_sel_hi:[1,1,0] neg_lo:[0,0,1] neg_hi:[0,0,1]
	v_pk_fma_f32 v[12:13], v[0:1], v[12:13], v[28:29] op_sel:[0,0,1] op_sel_hi:[1,1,0]
	s_nop 0
	v_mov_b32_e32 v31, v13
	s_waitcnt vmcnt(62)
	v_pk_add_f32 v[12:13], v[58:59], v[30:31]
	global_store_dword v[26:27], v12, off sc1
	global_store_dword v[26:27], v13, off offset:256 sc1
	v_pk_mul_f32 v[26:27], v[2:3], v[12:13]
	s_nop 0
	v_pk_fma_f32 v[28:29], v[0:1], v[12:13], v[26:27] op_sel:[0,0,1] op_sel_hi:[1,1,0] neg_lo:[0,0,1] neg_hi:[0,0,1]
	v_pk_fma_f32 v[12:13], v[0:1], v[12:13], v[26:27] op_sel:[0,0,1] op_sel_hi:[1,1,0]
	s_nop 0
	v_mov_b32_e32 v29, v13
	v_pk_add_f32 v[12:13], v[54:55], v[28:29]
	global_store_dword v[24:25], v12, off sc1
	global_store_dword v[24:25], v13, off offset:256 sc1
	v_pk_mul_f32 v[24:25], v[2:3], v[12:13]
	s_nop 0
	v_pk_fma_f32 v[26:27], v[0:1], v[12:13], v[24:25] op_sel:[0,0,1] op_sel_hi:[1,1,0] neg_lo:[0,0,1] neg_hi:[0,0,1]
	v_pk_fma_f32 v[12:13], v[0:1], v[12:13], v[24:25] op_sel:[0,0,1] op_sel_hi:[1,1,0]
	s_nop 0
	v_mov_b32_e32 v27, v13
	s_waitcnt vmcnt(62)
	v_pk_add_f32 v[12:13], v[50:51], v[26:27]
	global_store_dword v[22:23], v12, off sc1
	global_store_dword v[22:23], v13, off offset:256 sc1
	v_pk_mul_f32 v[22:23], v[2:3], v[12:13]
	s_nop 0
	v_pk_fma_f32 v[24:25], v[0:1], v[12:13], v[22:23] op_sel:[0,0,1] op_sel_hi:[1,1,0] neg_lo:[0,0,1] neg_hi:[0,0,1]
	v_pk_fma_f32 v[12:13], v[0:1], v[12:13], v[22:23] op_sel:[0,0,1] op_sel_hi:[1,1,0]
	s_nop 0
	v_mov_b32_e32 v25, v13
	v_pk_add_f32 v[12:13], v[46:47], v[24:25]
	global_store_dword v[20:21], v12, off sc1
	global_store_dword v[20:21], v13, off offset:256 sc1
	v_pk_mul_f32 v[20:21], v[2:3], v[12:13]
	s_nop 0
	v_pk_fma_f32 v[22:23], v[0:1], v[12:13], v[20:21] op_sel:[0,0,1] op_sel_hi:[1,1,0] neg_lo:[0,0,1] neg_hi:[0,0,1]
	v_pk_fma_f32 v[12:13], v[0:1], v[12:13], v[20:21] op_sel:[0,0,1] op_sel_hi:[1,1,0]
	s_nop 0
	v_mov_b32_e32 v23, v13
	s_waitcnt vmcnt(62)
	v_pk_add_f32 v[12:13], v[42:43], v[22:23]
	global_store_dword v[18:19], v12, off sc1
	global_store_dword v[18:19], v13, off offset:256 sc1
	v_pk_mul_f32 v[18:19], v[2:3], v[12:13]
	s_nop 0
	v_pk_fma_f32 v[20:21], v[0:1], v[12:13], v[18:19] op_sel:[0,0,1] op_sel_hi:[1,1,0] neg_lo:[0,0,1] neg_hi:[0,0,1]
	v_pk_fma_f32 v[12:13], v[0:1], v[12:13], v[18:19] op_sel:[0,0,1] op_sel_hi:[1,1,0]
	s_nop 0
	v_mov_b32_e32 v21, v13
	v_pk_add_f32 v[12:13], v[40:41], v[20:21]
	global_store_dword v[16:17], v12, off sc1
	global_store_dword v[16:17], v13, off offset:256 sc1
	v_pk_mul_f32 v[16:17], v[2:3], v[12:13]
	s_nop 0
	v_pk_fma_f32 v[18:19], v[0:1], v[12:13], v[16:17] op_sel:[0,0,1] op_sel_hi:[1,1,0] neg_lo:[0,0,1] neg_hi:[0,0,1]
	v_pk_fma_f32 v[12:13], v[0:1], v[12:13], v[16:17] op_sel:[0,0,1] op_sel_hi:[1,1,0]
	s_nop 0
	v_mov_b32_e32 v19, v13
	s_waitcnt vmcnt(62)
	v_pk_add_f32 v[12:13], v[36:37], v[18:19]
	global_store_dword v[14:15], v12, off sc1
	global_store_dword v[14:15], v13, off offset:256 sc1
	v_pk_mul_f32 v[14:15], v[2:3], v[12:13]
	s_nop 0
	v_pk_fma_f32 v[16:17], v[0:1], v[12:13], v[14:15] op_sel:[0,0,1] op_sel_hi:[1,1,0] neg_lo:[0,0,1] neg_hi:[0,0,1]
	v_pk_fma_f32 v[12:13], v[0:1], v[12:13], v[14:15] op_sel:[0,0,1] op_sel_hi:[1,1,0]
	s_nop 0
	v_mov_b32_e32 v17, v13
	v_pk_add_f32 v[12:13], v[78:79], v[16:17]
	s_cbranch_scc0 .LBB0_1386
